# resid epilogue output stage: second-half LayerNorm affine and shift/scale values prefetched at stage start, no mid-stage store drain
# speedup vs baseline: 1.0139x; 1.0046x over previous
.LBB0_946:
	s_or_b64 exec, exec, s[2:3]
	s_lshl_b32 s2, s17, 10
	s_mov_b32 s3, s69
	s_lshl_b64 s[2:3], s[2:3], 2
	s_add_u32 s2, s80, s2
	s_addc_u32 s3, s81, s3
	v_lshl_add_u64 v[2:3], v[242:243], 2, s[2:3]
	s_mov_b64 s[2:3], 0x55ac100
	v_lshl_add_u64 v[106:107], v[2:3], 0, s[2:3]
	s_mov_b32 s2, 0x55ac000
	v_add_co_u32_e32 v4, vcc, s2, v2
	s_mov_b64 s[2:3], 0x55b4100
	s_nop 0
	v_addc_co_u32_e32 v5, vcc, 0, v3, vcc
	v_lshl_add_u64 v[108:109], v[2:3], 0, s[2:3]
	v_add_co_u32_e32 v2, vcc, 0x55b4000, v2
	s_waitcnt lgkmcnt(0)
	s_barrier
	s_nop 0
	v_addc_co_u32_e32 v3, vcc, 0, v3, vcc
	flat_load_dwordx4 v[12:15], v[4:5] offset:256
	flat_load_dwordx4 v[16:19], v[2:3] offset:256
	s_nop 0
	flat_load_dwordx4 v[4:7], v[106:107] offset:16
	flat_load_dwordx4 v[8:11], v[108:109] offset:16
	flat_load_dwordx4 v[196:199], v[106:107] offset:512
	flat_load_dwordx4 v[200:203], v[106:107] offset:528
	flat_load_dwordx4 v[204:207], v[108:109] offset:512
	flat_load_dwordx2 v[208:209], v[108:109] offset:528
	flat_load_dwordx2 v[218:219], v[108:109] offset:536
	s_cmp_lg_u64 s[8:9], 0
	s_cselect_b64 s[2:3], -1, 0
	s_cmp_eq_u64 s[8:9], 0
	s_cbranch_scc1 .LBB0_948
	s_lshl_b64 s[4:5], s[68:69], 2
	s_add_u32 s4, s8, s4
	s_addc_u32 s5, s9, s5
	v_lshl_add_u64 v[2:3], v[242:243], 2, s[4:5]
	v_add_co_u32_e32 v24, vcc, 0x1000, v2
	s_nop 1
	v_addc_co_u32_e32 v25, vcc, 0, v3, vcc
	flat_load_dwordx4 v[20:23], v[24:25]
	s_nop 0
	flat_load_dwordx4 v[24:27], v[24:25] offset:16
	s_nop 0
	flat_load_dwordx4 v[32:35], v[2:3]
	flat_load_dwordx4 v[36:39], v[2:3] offset:16
	s_and_b64 vcc, exec, s[0:1]
	s_cbranch_vccz .Lap_h0_s
	v_add_co_u32_e32 v132, vcc, 0x1000, v2
	s_nop 1
	v_addc_co_u32_e32 v133, vcc, 0, v3, vcc
	flat_load_dwordx4 v[166:169], v[132:133] offset:512
	flat_load_dwordx4 v[170:173], v[132:133] offset:528
	flat_load_dwordx4 v[178:181], v[2:3] offset:512
	flat_load_dwordx4 v[182:185], v[2:3] offset:528
	s_branch .Lap_h0_a
.Lap_h0_s:
	v_add_co_u32_e32 v132, vcc, 0x6000, v2
	s_nop 1
	v_addc_co_u32_e32 v133, vcc, 0, v3, vcc
	v_add_co_u32_e32 v134, vcc, 0x7000, v2
	s_nop 1
	v_addc_co_u32_e32 v135, vcc, 0, v3, vcc
	flat_load_dwordx4 v[166:169], v[134:135]
	flat_load_dwordx4 v[170:173], v[134:135] offset:16
	flat_load_dwordx4 v[178:181], v[132:133]
	flat_load_dwordx4 v[182:185], v[132:133] offset:16

.LBB0_979:
	v_mov_b64_e32 v[12:13], v[196:197]
	v_mov_b64_e32 v[14:15], v[198:199]
	v_mov_b64_e32 v[4:5], v[200:201]
	v_mov_b64_e32 v[6:7], v[202:203]
	v_mov_b64_e32 v[16:17], v[204:205]
	v_mov_b64_e32 v[18:19], v[206:207]
	v_mov_b64_e32 v[8:9], v[208:209]
	v_mov_b64_e32 v[10:11], v[218:219]
	s_and_b64 vcc, exec, s[4:5]
	s_cbranch_vccnz .LBB0_987
	s_lshl_b64 s[2:3], s[68:69], 2
	s_add_u32 s2, s8, s2
	s_addc_u32 s3, s9, s3
	v_lshl_add_u64 v[2:3], v[242:243], 2, s[2:3]
	v_add_co_u32_e32 v24, vcc, 0x1000, v2
	s_nop 1
	v_addc_co_u32_e32 v25, vcc, 0, v3, vcc
	s_and_b64 vcc, exec, s[0:1]
	s_cbranch_vccz .Lap_h1_s
	v_pk_add_f32 v[42:43], v[168:169], 1.0 op_sel_hi:[1,0]
	v_pk_add_f32 v[40:41], v[166:167], 1.0 op_sel_hi:[1,0]
	v_pk_add_f32 v[50:51], v[172:173], 1.0 op_sel_hi:[1,0]
	v_pk_add_f32 v[48:49], v[170:171], 1.0 op_sel_hi:[1,0]
	v_mov_b64_e32 v[24:25], v[178:179]
	v_mov_b64_e32 v[26:27], v[180:181]
	v_mov_b64_e32 v[32:33], v[182:183]
	v_mov_b64_e32 v[34:35], v[184:185]
	s_branch .LBB0_988
.Lap_h1_s:
	flat_load_dwordx4 v[20:23], v[24:25] offset:512
	flat_load_dwordx4 v[28:31], v[24:25] offset:528
	s_nop 0
	flat_load_dwordx4 v[24:27], v[2:3] offset:512
	flat_load_dwordx4 v[32:35], v[2:3] offset:528
	s_and_b64 vcc, exec, s[0:1]
	s_cbranch_vccnz .Lap_h1_a
	v_add_co_u32_e32 v132, vcc, 0x6000, v2
	s_nop 1
	v_addc_co_u32_e32 v133, vcc, 0, v3, vcc
	v_add_co_u32_e32 v134, vcc, 0x7000, v2
	s_nop 1
	v_addc_co_u32_e32 v135, vcc, 0, v3, vcc
	flat_load_dwordx4 v[166:169], v[134:135] offset:512
	flat_load_dwordx4 v[170:173], v[134:135] offset:528
	flat_load_dwordx4 v[178:181], v[132:133] offset:512
	flat_load_dwordx4 v[182:185], v[132:133] offset:528

.LBB0_988:
	ds_read_b64 v[2:3], v110 offset:8192
	s_and_b64 vcc, exec, s[4:5]
	v_add_u32_e32 v0, v111, v99
	s_waitcnt lgkmcnt(0)
	v_sub_f32_e32 v21, v239, v2
	v_sub_f32_e32 v20, v238, v2
	v_sub_f32_e32 v23, v241, v2
	v_sub_f32_e32 v22, v240, v2
	v_pk_mul_f32 v[22:23], v[2:3], v[22:23] op_sel:[1,0]
	v_pk_mul_f32 v[20:21], v[2:3], v[20:21] op_sel:[1,0]
	v_pk_fma_f32 v[52:53], v[12:13], v[22:23], v[16:17]
	v_pk_fma_f32 v[54:55], v[14:15], v[20:21], v[18:19]
	v_sub_f32_e32 v21, v231, v2
	v_sub_f32_e32 v20, v230, v2
	v_sub_f32_e32 v23, v233, v2
	v_sub_f32_e32 v22, v232, v2
	v_pk_mul_f32 v[22:23], v[2:3], v[22:23] op_sel:[1,0]
	v_pk_mul_f32 v[2:3], v[2:3], v[20:21] op_sel:[1,0]
	v_pk_fma_f32 v[56:57], v[4:5], v[22:23], v[8:9]
	v_pk_fma_f32 v[58:59], v[6:7], v[2:3], v[10:11]
	s_cbranch_vccnz .LBB0_1032
	v_mov_b64_e32 v[20:21], v[24:25]
	v_mov_b64_e32 v[28:29], v[32:33]
	v_mov_b64_e32 v[36:37], v[40:41]
	v_mov_b64_e32 v[44:45], v[48:49]
	s_and_b64 vcc, exec, s[0:1]
	v_mov_b64_e32 v[22:23], v[26:27]
	v_mov_b64_e32 v[30:31], v[34:35]
	v_mov_b64_e32 v[38:39], v[42:43]
	v_mov_b64_e32 v[46:47], v[50:51]
	v_bfrev_b32_e32 v220, 0.5
	v_mov_b32_e32 v222, 0x2400
	s_cbranch_vccnz .LBB0_991
	v_add_u32_e32 v2, 0xffffe000, v249
	v_lshrrev_b32_e32 v2, 10, v2
	s_movk_i32 s2, 0x1800
	v_mad_u32_u24 v2, v2, s2, s2
	s_movk_i32 s2, 0x1fff
	v_cmp_lt_i32_e32 vcc, s2, v249
	v_mov_b32_e32 v3, v1
	s_nop 0
	v_cndmask_b32_e32 v2, 0, v2, vcc
	v_cmp_ne_u32_e32 vcc, s68, v2
	v_cndmask_b32_e32 v38, v144, v168, vcc
	v_cndmask_b32_e32 v39, v145, v169, vcc
	v_cndmask_b32_e32 v36, v142, v166, vcc
	v_cndmask_b32_e32 v37, v143, v167, vcc
	v_cndmask_b32_e32 v46, v148, v172, vcc
	v_cndmask_b32_e32 v47, v149, v173, vcc
	v_cndmask_b32_e32 v44, v146, v170, vcc
	v_cndmask_b32_e32 v45, v147, v171, vcc
	v_cndmask_b32_e32 v20, v154, v178, vcc
	v_cndmask_b32_e32 v21, v155, v179, vcc
	v_cndmask_b32_e32 v22, v156, v180, vcc
	v_cndmask_b32_e32 v23, v157, v181, vcc
	v_cndmask_b32_e32 v28, v158, v182, vcc
	v_cndmask_b32_e32 v29, v159, v183, vcc
	v_cndmask_b32_e32 v30, v160, v184, vcc
	v_cndmask_b32_e32 v31, v161, v185, vcc
